# FFN-down context-row tiles (64x64): 4-slot LDS ring with prefetch distance 3 + batched residual epilogue
# speedup vs baseline: 1.0186x; 1.0099x over previous
; #define TIDX opaque_tid()
; template <int AI, int BI>
; DI void gemm_tile(const u16* __restrict__ A, int lda, const u16* __restrict__ B, int ldb, int nk, bool swap,
;                   f32x16 (&acc)[AI][BI], char* lds) {
;   const int tid = TIDX, lane = tid & 63, wid = tid >> 6;
;   gemm_stage<AI, BI>(A, lda, B, ldb, lds, tid);
;   asm volatile("s_waitcnt vmcnt(0)" ::: "memory");
;   __syncthreads();
;   const int wa = wid >> 1, wb = wid & 1, r = lane & 31, h = lane >> 5, sw = (r >> 1) & 7;
;   const int offA = (swap ? 16384 : 0) + (wa * 32 * AI + r) * 128;
;   const int offB = (swap ? 0 : 16384) + (wb * 32 * BI + r) * 128;
;   for (int kt = 0; kt < nk; ++kt) {
;     const char* cur = lds + (kt & 1) * 32768;
;     if (kt + 1 < nk) gemm_stage<AI, BI>(A + (kt + 1) * 64, lda, B + (kt + 1) * 64, ldb, lds + ((kt + 1) & 1) * 32768, tid);
; template <int AI, int BI>
; DI void dn_tile(const Params& p, char* wsb, int layer, int sub, bool final_out, int m0, int n0, char* lds) {
;   const u16* HID = (const u16*)(wsb + OFF_HID);
;   const u16* W = (const u16*)(wsb + OFF_W) + (sub ? W_D1 : W_D0);
;   float* xs = (float*)(wsb + OFF_XS);
;   const float* mods = (const float*)(wsb + OFF_MODS) + (size_t)layer * 9 * 9216;
;   const int lane = TIDX & 63, wid = TIDX >> 6, wa = wid >> 1, wb = wid & 1, r = lane & 31, h = lane >> 5;
;   f32x16 acc[AI][BI]; zero_acc<AI, BI>(acc);
;   gemm_tile<AI, BI>(HID + (size_t)m0 * 2816, 2816, W + (size_t)n0 * 2816, 2816, 44, false, acc, lds);
.LBB0_478:
	v_readlane_b32 s8, v244, 61
	v_readlane_b32 s9, v244, 62
	s_andn2_b64 vcc, exec, s[8:9]
	s_nop 0
	v_cndmask_b32_e64 v0, 0, 1, s[8:9]
	v_cmp_ne_u32_e64 s[10:11], 1, v0
	s_nop 1
	v_writelane_b32 v242, s10, 5
	s_nop 1
	v_writelane_b32 v242, s11, 6
	s_cbranch_vccnz .LBB0_483
	s_add_u32 s8, s13, 0x4e000
	s_addc_u32 s9, s18, 0
	v_readlane_b32 s10, v243, 12
	s_add_u32 s18, s10, s12
	v_readlane_b32 s10, v243, 13
	s_addc_u32 s28, s10, 0
	v_readlane_b32 s10, v243, 16
	s_add_u32 s10, s10, s12
	v_readlane_b32 s11, v243, 17
	s_addc_u32 s11, s11, 0
	v_readlane_b32 s29, v243, 19
	v_readlane_b32 s34, v243, 18
	s_cmpk_lg_u32 s92, 0x200
	s_cbranch_scc1 .LBB0_480
	s_barrier
	s_lshr_b32 s70, s34, 4
	s_and_b32 s70, s70, 24
	s_and_b32 s72, s34, 7
	s_or_b32 s70, s70, s72
	s_lshl_b32 s70, s70, 6
	s_bitset1_b32 s70, 14
	s_lshl_b32 s71, s34, 3
	s_and_b32 s71, s71, 0x3c0
	s_mul_i32 s72, s70, 0x1600
	s_add_u32 s64, s14, s72
	s_addc_u32 s65, s15, 0
	s_mul_i32 s72, s71, 0x1600
	s_add_u32 s66, s16, s72
	s_addc_u32 s67, s17, 0
	v_and_b32_e32 v106, 31, v178
	v_bfe_u32 v107, v178, 5, 1
	v_bfe_u32 v108, v178, 1, 3
	v_bfe_u32 v109, v178, 7, 1
	v_lshl_add_u32 v109, v109, 5, v106
	v_lshlrev_b32_e32 v109, 7, v109
	v_bfe_u32 v0, v178, 6, 1
	v_lshl_add_u32 v0, v0, 5, v106
	v_lshlrev_b32_e32 v0, 7, v0
	v_add_u32_e32 v0, 0x2000, v0
	v_mov_b32_e32 v106, v107
	v_xor_b32_e32 v106, v106, v108
	v_lshlrev_b32_e32 v106, 4, v106
	v_add_u32_e32 v96, v109, v106
	v_add_u32_e32 v100, v0, v106
	v_add_u32_e32 v106, 2, v107
	v_xor_b32_e32 v106, v106, v108
	v_lshlrev_b32_e32 v106, 4, v106
	v_add_u32_e32 v97, v109, v106
	v_add_u32_e32 v101, v0, v106
	v_add_u32_e32 v106, 4, v107
	v_xor_b32_e32 v106, v106, v108
	v_lshlrev_b32_e32 v106, 4, v106
	v_add_u32_e32 v98, v109, v106
	v_add_u32_e32 v102, v0, v106
	v_add_u32_e32 v106, 6, v107
	v_xor_b32_e32 v106, v106, v108
	v_lshlrev_b32_e32 v106, 4, v106
	v_add_u32_e32 v99, v109, v106
	v_add_u32_e32 v103, v0, v106
	v_lshrrev_b32_e32 v106, 3, v178
	v_mul_u32_u24_e32 v106, 0x1600, v106
	v_and_b32_e32 v107, 7, v178
	v_bfe_u32 v108, v178, 4, 3
	v_xor_b32_e32 v107, v107, v108
	v_lshlrev_b32_e32 v107, 4, v107
	v_add_u32_e32 v104, v106, v107
	v_add_u32_e32 v105, 0x2c000, v104
	v_lshrrev_b32_e32 v106, 6, v178
	s_nop 1
	v_readfirstlane_b32 s68, v106
	s_lshl_b32 s68, s68, 10
	v_mov_b32_e32 v2, 0
	v_mov_b32_e32 v3, 0
	v_mov_b32_e32 v4, 0
	v_mov_b32_e32 v5, 0
	v_mov_b32_e32 v6, 0
	v_mov_b32_e32 v7, 0
	v_mov_b32_e32 v8, 0
	v_mov_b32_e32 v9, 0
	v_mov_b32_e32 v10, 0
	v_mov_b32_e32 v11, 0
	v_mov_b32_e32 v12, 0
	v_mov_b32_e32 v13, 0
	v_mov_b32_e32 v14, 0
	v_mov_b32_e32 v15, 0
	v_mov_b32_e32 v16, 0
	v_mov_b32_e32 v17, 0
	s_add_u32 m0, s68, 0
	s_nop 0
	global_load_lds_dwordx4 v104, s[64:65]
	s_add_u32 m0, s68, 4096
	s_nop 0
	global_load_lds_dwordx4 v105, s[64:65]
	s_add_u32 m0, s68, 8192
	s_nop 0
	global_load_lds_dwordx4 v104, s[66:67]
	s_add_u32 m0, s68, 12288
	s_nop 0
	global_load_lds_dwordx4 v105, s[66:67]
	s_add_u32 s64, s64, 0x80
	s_addc_u32 s65, s65, 0
	s_add_u32 s66, s66, 0x80
	s_addc_u32 s67, s67, 0
	s_add_u32 m0, s68, 16384
	s_nop 0
	global_load_lds_dwordx4 v104, s[64:65]
	s_add_u32 m0, s68, 20480
	s_nop 0
	global_load_lds_dwordx4 v105, s[64:65]
	s_add_u32 m0, s68, 24576
	s_nop 0
	global_load_lds_dwordx4 v104, s[66:67]
	s_add_u32 m0, s68, 28672
	s_nop 0
	global_load_lds_dwordx4 v105, s[66:67]
	s_add_u32 s64, s64, 0x80
	s_addc_u32 s65, s65, 0
	s_add_u32 s66, s66, 0x80
	s_addc_u32 s67, s67, 0
	s_add_u32 m0, s68, 32768
	s_nop 0
	global_load_lds_dwordx4 v104, s[64:65]
	s_add_u32 m0, s68, 36864
	s_nop 0
	global_load_lds_dwordx4 v105, s[64:65]
	s_add_u32 m0, s68, 40960
	s_nop 0
	global_load_lds_dwordx4 v104, s[66:67]
	s_add_u32 m0, s68, 45056
	s_nop 0
	global_load_lds_dwordx4 v105, s[66:67]
	s_add_u32 s64, s64, 0x80
	s_addc_u32 s65, s65, 0
	s_add_u32 s66, s66, 0x80
	s_addc_u32 s67, s67, 0
	s_mov_b32 s69, 10
.Ldc1_kloop:
	s_waitcnt vmcnt(8)
	s_barrier
	s_add_u32 m0, s68, 49152
	s_nop 0
	global_load_lds_dwordx4 v104, s[64:65]
	s_add_u32 m0, s68, 53248
	s_nop 0
	global_load_lds_dwordx4 v105, s[64:65]
	s_add_u32 m0, s68, 57344
	s_nop 0
	global_load_lds_dwordx4 v104, s[66:67]
	s_add_u32 m0, s68, 61440
	s_nop 0
	global_load_lds_dwordx4 v105, s[66:67]
	s_add_u32 s64, s64, 0x80
	s_addc_u32 s65, s65, 0
	s_add_u32 s66, s66, 0x80
	s_addc_u32 s67, s67, 0
	ds_read_b128 v[64:67], v96 offset:0
	ds_read_b128 v[68:71], v100 offset:0
	ds_read_b128 v[72:75], v97 offset:0
	ds_read_b128 v[76:79], v101 offset:0
	ds_read_b128 v[80:83], v98 offset:0
	ds_read_b128 v[84:87], v102 offset:0
	ds_read_b128 v[88:91], v99 offset:0
	ds_read_b128 v[92:95], v103 offset:0
	s_waitcnt lgkmcnt(6)
	v_mfma_f32_32x32x16_bf16 v[2:17], v[64:67], v[68:71], v[2:17]
	s_waitcnt lgkmcnt(4)
	v_mfma_f32_32x32x16_bf16 v[2:17], v[72:75], v[76:79], v[2:17]
	s_waitcnt lgkmcnt(2)
	v_mfma_f32_32x32x16_bf16 v[2:17], v[80:83], v[84:87], v[2:17]
	s_waitcnt lgkmcnt(0)
	v_mfma_f32_32x32x16_bf16 v[2:17], v[88:91], v[92:95], v[2:17]
	s_waitcnt vmcnt(8)
	s_barrier
	s_add_u32 m0, s68, 0
	s_nop 0
	global_load_lds_dwordx4 v104, s[64:65]
	s_add_u32 m0, s68, 4096
	s_nop 0
	global_load_lds_dwordx4 v105, s[64:65]
	s_add_u32 m0, s68, 8192
	s_nop 0
	global_load_lds_dwordx4 v104, s[66:67]
	s_add_u32 m0, s68, 12288
	s_nop 0
	global_load_lds_dwordx4 v105, s[66:67]
	s_add_u32 s64, s64, 0x80
	s_addc_u32 s65, s65, 0
	s_add_u32 s66, s66, 0x80
	s_addc_u32 s67, s67, 0
	ds_read_b128 v[64:67], v96 offset:16384
	ds_read_b128 v[68:71], v100 offset:16384
	ds_read_b128 v[72:75], v97 offset:16384
	ds_read_b128 v[76:79], v101 offset:16384
	ds_read_b128 v[80:83], v98 offset:16384
	ds_read_b128 v[84:87], v102 offset:16384
	ds_read_b128 v[88:91], v99 offset:16384
	ds_read_b128 v[92:95], v103 offset:16384
	s_waitcnt lgkmcnt(6)
	v_mfma_f32_32x32x16_bf16 v[2:17], v[64:67], v[68:71], v[2:17]
	s_waitcnt lgkmcnt(4)
	v_mfma_f32_32x32x16_bf16 v[2:17], v[72:75], v[76:79], v[2:17]
	s_waitcnt lgkmcnt(2)
	v_mfma_f32_32x32x16_bf16 v[2:17], v[80:83], v[84:87], v[2:17]
	s_waitcnt lgkmcnt(0)
	v_mfma_f32_32x32x16_bf16 v[2:17], v[88:91], v[92:95], v[2:17]
	s_waitcnt vmcnt(8)
	s_barrier
; #define MFMA(a, b, c) __builtin_amdgcn_mfma_f32_32x32x16_bf16((a), (b), (c), 0, 0, 0)
; template <int AI, int BI>
; DI void gemm_tile(const u16* __restrict__ A, int lda, const u16* __restrict__ B, int ldb, int nk, bool swap,
;                   f32x16 (&acc)[AI][BI], char* lds) {
;     ...
;   for (int kt = 0; kt < nk; ++kt) {
;     const char* cur = lds + (kt & 1) * 32768;
;     if (kt + 1 < nk) gemm_stage<AI, BI>(A + (kt + 1) * 64, lda, B + (kt + 1) * 64, ldb, lds + ((kt + 1) & 1) * 32768, tid);
; #pragma unroll
;     for (int ks = 0; ks < 4; ++ks) {
;       const int co = ((ks * 2 + h) ^ sw) << 4;
;       s16x8 fa[AI], fb[BI];
; #pragma unroll
;       for (int i = 0; i < AI; ++i) fa[i] = *(const s16x8*)(cur + offA + i * 4096 + co);
; #pragma unroll
;       for (int i = 0; i < BI; ++i) fb[i] = *(const s16x8*)(cur + offB + i * 4096 + co);
; #pragma unroll
;       for (int i = 0; i < AI; ++i)
; #pragma unroll
;         for (int j = 0; j < BI; ++j) acc[i][j] = MFMA(fa[i], fb[j], acc[i][j]);
;     }
;     asm volatile("s_waitcnt vmcnt(0)" ::: "memory");
;     __syncthreads();
;   }
	s_add_u32 m0, s68, 16384
	s_nop 0
	global_load_lds_dwordx4 v104, s[64:65]
	s_add_u32 m0, s68, 20480
	s_nop 0
	global_load_lds_dwordx4 v105, s[64:65]
	s_add_u32 m0, s68, 24576
	s_nop 0
	global_load_lds_dwordx4 v104, s[66:67]
	s_add_u32 m0, s68, 28672
	s_nop 0
	global_load_lds_dwordx4 v105, s[66:67]
	s_add_u32 s64, s64, 0x80
	s_addc_u32 s65, s65, 0
	s_add_u32 s66, s66, 0x80
	s_addc_u32 s67, s67, 0
	ds_read_b128 v[64:67], v96 offset:32768
	ds_read_b128 v[68:71], v100 offset:32768
	ds_read_b128 v[72:75], v97 offset:32768
	ds_read_b128 v[76:79], v101 offset:32768
	ds_read_b128 v[80:83], v98 offset:32768
	ds_read_b128 v[84:87], v102 offset:32768
	ds_read_b128 v[88:91], v99 offset:32768
	ds_read_b128 v[92:95], v103 offset:32768
	s_waitcnt lgkmcnt(6)
	v_mfma_f32_32x32x16_bf16 v[2:17], v[64:67], v[68:71], v[2:17]
	s_waitcnt lgkmcnt(4)
	v_mfma_f32_32x32x16_bf16 v[2:17], v[72:75], v[76:79], v[2:17]
	s_waitcnt lgkmcnt(2)
	v_mfma_f32_32x32x16_bf16 v[2:17], v[80:83], v[84:87], v[2:17]
	s_waitcnt lgkmcnt(0)
	v_mfma_f32_32x32x16_bf16 v[2:17], v[88:91], v[92:95], v[2:17]
	s_waitcnt vmcnt(8)
	s_barrier
	s_add_u32 m0, s68, 32768
	s_nop 0
	global_load_lds_dwordx4 v104, s[64:65]
	s_add_u32 m0, s68, 36864
	s_nop 0
	global_load_lds_dwordx4 v105, s[64:65]
	s_add_u32 m0, s68, 40960
	s_nop 0
	global_load_lds_dwordx4 v104, s[66:67]
	s_add_u32 m0, s68, 45056
	s_nop 0
	global_load_lds_dwordx4 v105, s[66:67]
	s_add_u32 s64, s64, 0x80
	s_addc_u32 s65, s65, 0
	s_add_u32 s66, s66, 0x80
	s_addc_u32 s67, s67, 0
	ds_read_b128 v[64:67], v96 offset:49152
	ds_read_b128 v[68:71], v100 offset:49152
	ds_read_b128 v[72:75], v97 offset:49152
	ds_read_b128 v[76:79], v101 offset:49152
	ds_read_b128 v[80:83], v98 offset:49152
	ds_read_b128 v[84:87], v102 offset:49152
	ds_read_b128 v[88:91], v99 offset:49152
	ds_read_b128 v[92:95], v103 offset:49152
	s_waitcnt lgkmcnt(6)
	v_mfma_f32_32x32x16_bf16 v[2:17], v[64:67], v[68:71], v[2:17]
	s_waitcnt lgkmcnt(4)
	v_mfma_f32_32x32x16_bf16 v[2:17], v[72:75], v[76:79], v[2:17]
	s_waitcnt lgkmcnt(2)
	v_mfma_f32_32x32x16_bf16 v[2:17], v[80:83], v[84:87], v[2:17]
	s_waitcnt lgkmcnt(0)
	v_mfma_f32_32x32x16_bf16 v[2:17], v[88:91], v[92:95], v[2:17]
	s_sub_u32 s69, s69, 1
	s_cmp_lg_u32 s69, 0
	s_cbranch_scc1 .Ldc1_kloop
	s_waitcnt vmcnt(8)
	s_barrier
	s_add_u32 m0, s68, 49152
	s_nop 0
	global_load_lds_dwordx4 v104, s[64:65]
	s_add_u32 m0, s68, 53248
	s_nop 0
	global_load_lds_dwordx4 v105, s[64:65]
	s_add_u32 m0, s68, 57344
	s_nop 0
	global_load_lds_dwordx4 v104, s[66:67]
	s_add_u32 m0, s68, 61440
	s_nop 0
	global_load_lds_dwordx4 v105, s[66:67]
	s_add_u32 s64, s64, 0x80
	s_addc_u32 s65, s65, 0
	s_add_u32 s66, s66, 0x80
	s_addc_u32 s67, s67, 0
	ds_read_b128 v[64:67], v96 offset:0
	ds_read_b128 v[68:71], v100 offset:0
	ds_read_b128 v[72:75], v97 offset:0
	ds_read_b128 v[76:79], v101 offset:0
	ds_read_b128 v[80:83], v98 offset:0
	ds_read_b128 v[84:87], v102 offset:0
	ds_read_b128 v[88:91], v99 offset:0
	ds_read_b128 v[92:95], v103 offset:0
	s_waitcnt lgkmcnt(6)
	v_mfma_f32_32x32x16_bf16 v[2:17], v[64:67], v[68:71], v[2:17]
	s_waitcnt lgkmcnt(4)
	v_mfma_f32_32x32x16_bf16 v[2:17], v[72:75], v[76:79], v[2:17]
	s_waitcnt lgkmcnt(2)
	v_mfma_f32_32x32x16_bf16 v[2:17], v[80:83], v[84:87], v[2:17]
	s_waitcnt lgkmcnt(0)
	v_mfma_f32_32x32x16_bf16 v[2:17], v[88:91], v[92:95], v[2:17]
	s_waitcnt vmcnt(8)
	s_barrier
	ds_read_b128 v[64:67], v96 offset:16384
	ds_read_b128 v[68:71], v100 offset:16384
	ds_read_b128 v[72:75], v97 offset:16384
	ds_read_b128 v[76:79], v101 offset:16384
	ds_read_b128 v[80:83], v98 offset:16384
	ds_read_b128 v[84:87], v102 offset:16384
	ds_read_b128 v[88:91], v99 offset:16384
	ds_read_b128 v[92:95], v103 offset:16384
	s_waitcnt lgkmcnt(6)
	v_mfma_f32_32x32x16_bf16 v[2:17], v[64:67], v[68:71], v[2:17]
	s_waitcnt lgkmcnt(4)
	v_mfma_f32_32x32x16_bf16 v[2:17], v[72:75], v[76:79], v[2:17]
	s_waitcnt lgkmcnt(2)
	v_mfma_f32_32x32x16_bf16 v[2:17], v[80:83], v[84:87], v[2:17]
	s_waitcnt lgkmcnt(0)
	v_mfma_f32_32x32x16_bf16 v[2:17], v[88:91], v[92:95], v[2:17]
	s_waitcnt vmcnt(4)
	s_barrier
	ds_read_b128 v[64:67], v96 offset:32768
	ds_read_b128 v[68:71], v100 offset:32768
	ds_read_b128 v[72:75], v97 offset:32768
	ds_read_b128 v[76:79], v101 offset:32768
	ds_read_b128 v[80:83], v98 offset:32768
	ds_read_b128 v[84:87], v102 offset:32768
	ds_read_b128 v[88:91], v99 offset:32768
	ds_read_b128 v[92:95], v103 offset:32768
	s_waitcnt lgkmcnt(6)
	v_mfma_f32_32x32x16_bf16 v[2:17], v[64:67], v[68:71], v[2:17]
	s_waitcnt lgkmcnt(4)
	v_mfma_f32_32x32x16_bf16 v[2:17], v[72:75], v[76:79], v[2:17]
	s_waitcnt lgkmcnt(2)
	v_mfma_f32_32x32x16_bf16 v[2:17], v[80:83], v[84:87], v[2:17]
	s_waitcnt lgkmcnt(0)
	v_mfma_f32_32x32x16_bf16 v[2:17], v[88:91], v[92:95], v[2:17]
	s_waitcnt vmcnt(0)
	s_barrier
; #define GAS __attribute__((address_space(1)))
; DI int opaque0() { int z = 0; asm volatile("" : "+v"(z)); return z; }
; template <int AI, int BI>
; DI void dn_tile(const Params& p, char* wsb, int layer, int sub, bool final_out, int m0, int n0, char* lds) {
;     ...
;   const int m0e = m0 + opaque0();
;   const int mr = m0 < TL ? (m0 >> 11) : 8;
;   const float* gate = mods + (size_t)mr * 9216 + (2 + 6 * sub) * 1024;
;   GAS float* xsu = uptr(xs);
;   GAS float* outu = uptr(p.out);
; #pragma unroll
;   for (int bi = 0; bi < BI; ++bi) {
;     const int n = n0 + wb * 32 * BI + bi * 32 + r;
;     const float gv = 0.5f * gate[n];
;     const unsigned ib = (unsigned)((m0e + wa * 32 * AI + 4 * h) * 1024 + n);
; #pragma unroll
;     for (int ai = 0; ai < AI; ++ai)
; #pragma unroll
;       for (int reg = 0; reg < 16; ++reg) {
;         const unsigned idx = ib + (unsigned)((ai * 32 + (reg & 3) + 8 * (reg >> 2)) * 1024);
;         float v = xsu[idx] + gv * acc[ai][bi][reg];
;         if (final_out) outu[idx] = v; else xsu[idx] = v;
;         if ((reg & 7) == 7) __builtin_amdgcn_sched_barrier(0);
;       }
;   }
	ds_read_b128 v[64:67], v96 offset:49152
	ds_read_b128 v[68:71], v100 offset:49152
	ds_read_b128 v[72:75], v97 offset:49152
	ds_read_b128 v[76:79], v101 offset:49152
	ds_read_b128 v[80:83], v98 offset:49152
	ds_read_b128 v[84:87], v102 offset:49152
	ds_read_b128 v[88:91], v99 offset:49152
	ds_read_b128 v[92:95], v103 offset:49152
	s_waitcnt lgkmcnt(6)
	v_mfma_f32_32x32x16_bf16 v[2:17], v[64:67], v[68:71], v[2:17]
	s_waitcnt lgkmcnt(4)
	v_mfma_f32_32x32x16_bf16 v[2:17], v[72:75], v[76:79], v[2:17]
	s_waitcnt lgkmcnt(2)
	v_mfma_f32_32x32x16_bf16 v[2:17], v[80:83], v[84:87], v[2:17]
	s_waitcnt lgkmcnt(0)
	v_mfma_f32_32x32x16_bf16 v[2:17], v[88:91], v[92:95], v[2:17]
	s_nop 7
	s_nop 7
	v_and_b32_e32 v143, 31, v178
	v_lshrrev_b32_e32 v140, 1, v178
	v_and_b32_e32 v140, 32, v140
	v_or_b32_e32 v140, v140, v143
	v_bfe_u32 v143, v178, 5, 1
	v_bfe_u32 v139, v178, 7, 1
	v_lshlrev_b32_e32 v139, 5, v139
	v_lshl_add_u32 v139, v143, 2, v139
	v_lshl_add_u32 v139, v139, 10, v140
	v_lshlrev_b32_e32 v139, 2, v139
	v_add_u32_e32 v140, s71, v140
	v_lshlrev_b32_e32 v140, 2, v140
	global_load_dword v141, v140, s[8:9]
	s_lshl_b32 s82, s70, 10
	s_add_u32 s82, s82, s71
	s_lshl_b32 s82, s82, 2
	s_add_u32 s54, s6, s82
	s_addc_u32 s55, s7, 0
	s_mov_b64 s[80:81], s[54:55]
	global_load_dword v66, v139, s[80:81]
	s_add_u32 s80, s80, 4096
	s_addc_u32 s81, s81, 0
	global_load_dword v67, v139, s[80:81]
	s_add_u32 s80, s80, 4096
	s_addc_u32 s81, s81, 0
	global_load_dword v68, v139, s[80:81]
	s_add_u32 s80, s80, 4096
	s_addc_u32 s81, s81, 0
	global_load_dword v69, v139, s[80:81]
	s_add_u32 s80, s80, 20480
	s_addc_u32 s81, s81, 0
	global_load_dword v70, v139, s[80:81]
	s_add_u32 s80, s80, 4096
	s_addc_u32 s81, s81, 0
	global_load_dword v71, v139, s[80:81]
	s_add_u32 s80, s80, 4096
	s_addc_u32 s81, s81, 0
	global_load_dword v72, v139, s[80:81]
	s_add_u32 s80, s80, 4096
	s_addc_u32 s81, s81, 0
	global_load_dword v73, v139, s[80:81]
	s_add_u32 s80, s80, 20480
	s_addc_u32 s81, s81, 0
	global_load_dword v74, v139, s[80:81]
	s_add_u32 s80, s80, 4096
	s_addc_u32 s81, s81, 0
	global_load_dword v75, v139, s[80:81]
	s_add_u32 s80, s80, 4096
	s_addc_u32 s81, s81, 0
	global_load_dword v76, v139, s[80:81]
	s_add_u32 s80, s80, 4096
	s_addc_u32 s81, s81, 0
	global_load_dword v77, v139, s[80:81]
	s_add_u32 s80, s80, 20480
	s_addc_u32 s81, s81, 0
	global_load_dword v78, v139, s[80:81]
	s_add_u32 s80, s80, 4096
	s_addc_u32 s81, s81, 0
	global_load_dword v79, v139, s[80:81]
	s_add_u32 s80, s80, 4096
	s_addc_u32 s81, s81, 0
	global_load_dword v80, v139, s[80:81]
	s_add_u32 s80, s80, 4096
	s_addc_u32 s81, s81, 0
	global_load_dword v81, v139, s[80:81]
	s_waitcnt vmcnt(0)
	v_mul_f32_e32 v141, 0.5, v141
	v_fmac_f32_e32 v66, v2, v141
	v_fmac_f32_e32 v67, v3, v141
	v_fmac_f32_e32 v68, v4, v141
	v_fmac_f32_e32 v69, v5, v141
	v_fmac_f32_e32 v70, v6, v141
	v_fmac_f32_e32 v71, v7, v141
	v_fmac_f32_e32 v72, v8, v141
	v_fmac_f32_e32 v73, v9, v141
	v_fmac_f32_e32 v74, v10, v141
	v_fmac_f32_e32 v75, v11, v141
	v_fmac_f32_e32 v76, v12, v141
	v_fmac_f32_e32 v77, v13, v141
	v_fmac_f32_e32 v78, v14, v141
	v_fmac_f32_e32 v79, v15, v141
	v_fmac_f32_e32 v80, v16, v141
	v_fmac_f32_e32 v81, v17, v141
	s_mov_b64 s[80:81], s[54:55]
	global_store_dword v139, v66, s[80:81]
	s_add_u32 s80, s80, 4096
	s_addc_u32 s81, s81, 0
	global_store_dword v139, v67, s[80:81]
	s_add_u32 s80, s80, 4096
	s_addc_u32 s81, s81, 0
	global_store_dword v139, v68, s[80:81]
	s_add_u32 s80, s80, 4096
	s_addc_u32 s81, s81, 0
	global_store_dword v139, v69, s[80:81]
	s_add_u32 s80, s80, 20480
	s_addc_u32 s81, s81, 0
	global_store_dword v139, v70, s[80:81]
	s_add_u32 s80, s80, 4096
	s_addc_u32 s81, s81, 0
	global_store_dword v139, v71, s[80:81]
	s_add_u32 s80, s80, 4096
	s_addc_u32 s81, s81, 0
	global_store_dword v139, v72, s[80:81]
	s_add_u32 s80, s80, 4096
	s_addc_u32 s81, s81, 0
	global_store_dword v139, v73, s[80:81]
	s_add_u32 s80, s80, 20480
	s_addc_u32 s81, s81, 0
	global_store_dword v139, v74, s[80:81]
	s_add_u32 s80, s80, 4096
	s_addc_u32 s81, s81, 0
	global_store_dword v139, v75, s[80:81]
	s_add_u32 s80, s80, 4096
	s_addc_u32 s81, s81, 0
	global_store_dword v139, v76, s[80:81]
	s_add_u32 s80, s80, 4096
	s_addc_u32 s81, s81, 0
	global_store_dword v139, v77, s[80:81]
	s_add_u32 s80, s80, 20480
	s_addc_u32 s81, s81, 0
	global_store_dword v139, v78, s[80:81]
	s_add_u32 s80, s80, 4096
	s_addc_u32 s81, s81, 0
	global_store_dword v139, v79, s[80:81]
	s_add_u32 s80, s80, 4096
	s_addc_u32 s81, s81, 0
	global_store_dword v139, v80, s[80:81]
	s_add_u32 s80, s80, 4096
	s_addc_u32 s81, s81, 0
	global_store_dword v139, v81, s[80:81]
	s_branch .LBB0_483

; #define TIDX opaque_tid()
; template <int AI, int BI>
; DI void gemm_tile(const u16* __restrict__ A, int lda, const u16* __restrict__ B, int ldb, int nk, bool swap,
;                   f32x16 (&acc)[AI][BI], char* lds) {
;   const int tid = TIDX, lane = tid & 63, wid = tid >> 6;
;   gemm_stage<AI, BI>(A, lda, B, ldb, lds, tid);
;   asm volatile("s_waitcnt vmcnt(0)" ::: "memory");
;   __syncthreads();
;   const int wa = wid >> 1, wb = wid & 1, r = lane & 31, h = lane >> 5, sw = (r >> 1) & 7;
;   const int offA = (swap ? 16384 : 0) + (wa * 32 * AI + r) * 128;
;   const int offB = (swap ? 0 : 16384) + (wb * 32 * BI + r) * 128;
;   for (int kt = 0; kt < nk; ++kt) {
;     const char* cur = lds + (kt & 1) * 32768;
;     if (kt + 1 < nk) gemm_stage<AI, BI>(A + (kt + 1) * 64, lda, B + (kt + 1) * 64, ldb, lds + ((kt + 1) & 1) * 32768, tid);
; template <int AI, int BI>
; DI void dn_tile(const Params& p, char* wsb, int layer, int sub, bool final_out, int m0, int n0, char* lds) {
;   const u16* HID = (const u16*)(wsb + OFF_HID);
;   const u16* W = (const u16*)(wsb + OFF_W) + (sub ? W_D1 : W_D0);
;   float* xs = (float*)(wsb + OFF_XS);
;   const float* mods = (const float*)(wsb + OFF_MODS) + (size_t)layer * 9 * 9216;
;   const int lane = TIDX & 63, wid = TIDX >> 6, wa = wid >> 1, wb = wid & 1, r = lane & 31, h = lane >> 5;
;   f32x16 acc[AI][BI]; zero_acc<AI, BI>(acc);
;   gemm_tile<AI, BI>(HID + (size_t)m0 * 2816, 2816, W + (size_t)n0 * 2816, 2816, 44, false, acc, lds);
.LBB0_1522:
	v_readlane_b32 s6, v242, 5
	v_readlane_b32 s7, v242, 6
	s_and_b64 vcc, exec, s[6:7]
	s_cbranch_vccnz .LBB0_1527
	s_add_u32 s6, s34, 0x54000
	s_addc_u32 s7, s35, 0
	v_readlane_b32 s10, v243, 12
	s_add_u32 s14, s10, s29
	v_readlane_b32 s10, v243, 13
	s_addc_u32 s15, s10, 0
	v_readlane_b32 s10, v243, 27
	s_add_u32 s10, s10, s29
	v_readlane_b32 s11, v243, 28
	s_addc_u32 s11, s11, 0
	v_readlane_b32 s29, v243, 19
	v_readlane_b32 s34, v243, 18
	s_cmpk_lg_u32 s92, 0x200
	s_cbranch_scc1 .LBB0_1524
	s_barrier
	s_lshr_b32 s70, s34, 4
	s_and_b32 s70, s70, 24
	s_and_b32 s72, s34, 7
	s_or_b32 s70, s70, s72
	s_lshl_b32 s70, s70, 6
	s_bitset1_b32 s70, 14
	s_lshl_b32 s71, s34, 3
	s_and_b32 s71, s71, 0x3c0
	s_mul_i32 s72, s70, 0x1600
	s_add_u32 s64, s16, s72
	s_addc_u32 s65, s17, 0
	s_mul_i32 s72, s71, 0x1600
	s_add_u32 s66, s18, s72
	s_addc_u32 s67, s28, 0
	v_and_b32_e32 v106, 31, v178
	v_bfe_u32 v107, v178, 5, 1
	v_bfe_u32 v108, v178, 1, 3
	v_bfe_u32 v109, v178, 7, 1
	v_lshl_add_u32 v109, v109, 5, v106
	v_lshlrev_b32_e32 v109, 7, v109
	v_bfe_u32 v0, v178, 6, 1
	v_lshl_add_u32 v0, v0, 5, v106
	v_lshlrev_b32_e32 v0, 7, v0
	v_add_u32_e32 v0, 0x2000, v0
	v_mov_b32_e32 v106, v107
	v_xor_b32_e32 v106, v106, v108
	v_lshlrev_b32_e32 v106, 4, v106
	v_add_u32_e32 v96, v109, v106
	v_add_u32_e32 v100, v0, v106
	v_add_u32_e32 v106, 2, v107
	v_xor_b32_e32 v106, v106, v108
	v_lshlrev_b32_e32 v106, 4, v106
	v_add_u32_e32 v97, v109, v106
	v_add_u32_e32 v101, v0, v106
	v_add_u32_e32 v106, 4, v107
	v_xor_b32_e32 v106, v106, v108
	v_lshlrev_b32_e32 v106, 4, v106
	v_add_u32_e32 v98, v109, v106
	v_add_u32_e32 v102, v0, v106
	v_add_u32_e32 v106, 6, v107
	v_xor_b32_e32 v106, v106, v108
	v_lshlrev_b32_e32 v106, 4, v106
	v_add_u32_e32 v99, v109, v106
	v_add_u32_e32 v103, v0, v106
	v_lshrrev_b32_e32 v106, 3, v178
	v_mul_u32_u24_e32 v106, 0x1600, v106
	v_and_b32_e32 v107, 7, v178
	v_bfe_u32 v108, v178, 4, 3
	v_xor_b32_e32 v107, v107, v108
	v_lshlrev_b32_e32 v107, 4, v107
	v_add_u32_e32 v104, v106, v107
	v_add_u32_e32 v105, 0x2c000, v104
	v_lshrrev_b32_e32 v106, 6, v178
	s_nop 1
	v_readfirstlane_b32 s68, v106
	s_lshl_b32 s68, s68, 10
	v_mov_b32_e32 v2, 0
	v_mov_b32_e32 v3, 0
	v_mov_b32_e32 v4, 0
	v_mov_b32_e32 v5, 0
	v_mov_b32_e32 v6, 0
	v_mov_b32_e32 v7, 0
	v_mov_b32_e32 v8, 0
	v_mov_b32_e32 v9, 0
	v_mov_b32_e32 v10, 0
	v_mov_b32_e32 v11, 0
	v_mov_b32_e32 v12, 0
	v_mov_b32_e32 v13, 0
	v_mov_b32_e32 v14, 0
	v_mov_b32_e32 v15, 0
	v_mov_b32_e32 v16, 0
	v_mov_b32_e32 v17, 0
	s_add_u32 m0, s68, 0
	s_nop 0
	global_load_lds_dwordx4 v104, s[64:65]
	s_add_u32 m0, s68, 4096
	s_nop 0
	global_load_lds_dwordx4 v105, s[64:65]
	s_add_u32 m0, s68, 8192
	s_nop 0
	global_load_lds_dwordx4 v104, s[66:67]
	s_add_u32 m0, s68, 12288
	s_nop 0
	global_load_lds_dwordx4 v105, s[66:67]
	s_add_u32 s64, s64, 0x80
	s_addc_u32 s65, s65, 0
	s_add_u32 s66, s66, 0x80
	s_addc_u32 s67, s67, 0
	s_add_u32 m0, s68, 16384
	s_nop 0
	global_load_lds_dwordx4 v104, s[64:65]
	s_add_u32 m0, s68, 20480
	s_nop 0
	global_load_lds_dwordx4 v105, s[64:65]
	s_add_u32 m0, s68, 24576
	s_nop 0
	global_load_lds_dwordx4 v104, s[66:67]
	s_add_u32 m0, s68, 28672
	s_nop 0
	global_load_lds_dwordx4 v105, s[66:67]
	s_add_u32 s64, s64, 0x80
	s_addc_u32 s65, s65, 0
	s_add_u32 s66, s66, 0x80
	s_addc_u32 s67, s67, 0
	s_add_u32 m0, s68, 32768
	s_nop 0
	global_load_lds_dwordx4 v104, s[64:65]
	s_add_u32 m0, s68, 36864
	s_nop 0
	global_load_lds_dwordx4 v105, s[64:65]
	s_add_u32 m0, s68, 40960
	s_nop 0
	global_load_lds_dwordx4 v104, s[66:67]
	s_add_u32 m0, s68, 45056
	s_nop 0
	global_load_lds_dwordx4 v105, s[66:67]
	s_add_u32 s64, s64, 0x80
	s_addc_u32 s65, s65, 0
	s_add_u32 s66, s66, 0x80
	s_addc_u32 s67, s67, 0
	s_mov_b32 s69, 10
.Ldc2_kloop:
	s_waitcnt vmcnt(8)
	s_barrier
	s_add_u32 m0, s68, 49152
	s_nop 0
	global_load_lds_dwordx4 v104, s[64:65]
	s_add_u32 m0, s68, 53248
	s_nop 0
	global_load_lds_dwordx4 v105, s[64:65]
	s_add_u32 m0, s68, 57344
	s_nop 0
	global_load_lds_dwordx4 v104, s[66:67]
	s_add_u32 m0, s68, 61440
	s_nop 0
	global_load_lds_dwordx4 v105, s[66:67]
	s_add_u32 s64, s64, 0x80
	s_addc_u32 s65, s65, 0
	s_add_u32 s66, s66, 0x80
	s_addc_u32 s67, s67, 0
	ds_read_b128 v[64:67], v96 offset:0
	ds_read_b128 v[68:71], v100 offset:0
	ds_read_b128 v[72:75], v97 offset:0
	ds_read_b128 v[76:79], v101 offset:0
	ds_read_b128 v[80:83], v98 offset:0
	ds_read_b128 v[84:87], v102 offset:0
	ds_read_b128 v[88:91], v99 offset:0
	ds_read_b128 v[92:95], v103 offset:0
	s_waitcnt lgkmcnt(6)
	v_mfma_f32_32x32x16_bf16 v[2:17], v[64:67], v[68:71], v[2:17]
	s_waitcnt lgkmcnt(4)
	v_mfma_f32_32x32x16_bf16 v[2:17], v[72:75], v[76:79], v[2:17]
	s_waitcnt lgkmcnt(2)
	v_mfma_f32_32x32x16_bf16 v[2:17], v[80:83], v[84:87], v[2:17]
	s_waitcnt lgkmcnt(0)
	v_mfma_f32_32x32x16_bf16 v[2:17], v[88:91], v[92:95], v[2:17]
	s_waitcnt vmcnt(8)
	s_barrier
	s_add_u32 m0, s68, 0
	s_nop 0
	global_load_lds_dwordx4 v104, s[64:65]
	s_add_u32 m0, s68, 4096
	s_nop 0
	global_load_lds_dwordx4 v105, s[64:65]
	s_add_u32 m0, s68, 8192
	s_nop 0
	global_load_lds_dwordx4 v104, s[66:67]
	s_add_u32 m0, s68, 12288
	s_nop 0
	global_load_lds_dwordx4 v105, s[66:67]
	s_add_u32 s64, s64, 0x80
	s_addc_u32 s65, s65, 0
	s_add_u32 s66, s66, 0x80
	s_addc_u32 s67, s67, 0
	ds_read_b128 v[64:67], v96 offset:16384
	ds_read_b128 v[68:71], v100 offset:16384
	ds_read_b128 v[72:75], v97 offset:16384
	ds_read_b128 v[76:79], v101 offset:16384
	ds_read_b128 v[80:83], v98 offset:16384
	ds_read_b128 v[84:87], v102 offset:16384
	ds_read_b128 v[88:91], v99 offset:16384
	ds_read_b128 v[92:95], v103 offset:16384
	s_waitcnt lgkmcnt(6)
	v_mfma_f32_32x32x16_bf16 v[2:17], v[64:67], v[68:71], v[2:17]
	s_waitcnt lgkmcnt(4)
	v_mfma_f32_32x32x16_bf16 v[2:17], v[72:75], v[76:79], v[2:17]
	s_waitcnt lgkmcnt(2)
	v_mfma_f32_32x32x16_bf16 v[2:17], v[80:83], v[84:87], v[2:17]
	s_waitcnt lgkmcnt(0)
	v_mfma_f32_32x32x16_bf16 v[2:17], v[88:91], v[92:95], v[2:17]
	s_waitcnt vmcnt(8)
	s_barrier
; #define MFMA(a, b, c) __builtin_amdgcn_mfma_f32_32x32x16_bf16((a), (b), (c), 0, 0, 0)
; template <int AI, int BI>
; DI void gemm_tile(const u16* __restrict__ A, int lda, const u16* __restrict__ B, int ldb, int nk, bool swap,
;                   f32x16 (&acc)[AI][BI], char* lds) {
;     ...
;   for (int kt = 0; kt < nk; ++kt) {
;     const char* cur = lds + (kt & 1) * 32768;
;     if (kt + 1 < nk) gemm_stage<AI, BI>(A + (kt + 1) * 64, lda, B + (kt + 1) * 64, ldb, lds + ((kt + 1) & 1) * 32768, tid);
; #pragma unroll
;     for (int ks = 0; ks < 4; ++ks) {
;       const int co = ((ks * 2 + h) ^ sw) << 4;
;       s16x8 fa[AI], fb[BI];
; #pragma unroll
;       for (int i = 0; i < AI; ++i) fa[i] = *(const s16x8*)(cur + offA + i * 4096 + co);
; #pragma unroll
;       for (int i = 0; i < BI; ++i) fb[i] = *(const s16x8*)(cur + offB + i * 4096 + co);
; #pragma unroll
;       for (int i = 0; i < AI; ++i)
; #pragma unroll
;         for (int j = 0; j < BI; ++j) acc[i][j] = MFMA(fa[i], fb[j], acc[i][j]);
;     }
;     asm volatile("s_waitcnt vmcnt(0)" ::: "memory");
;     __syncthreads();
;   }
	s_add_u32 m0, s68, 16384
	s_nop 0
	global_load_lds_dwordx4 v104, s[64:65]
	s_add_u32 m0, s68, 20480
	s_nop 0
	global_load_lds_dwordx4 v105, s[64:65]
	s_add_u32 m0, s68, 24576
	s_nop 0
	global_load_lds_dwordx4 v104, s[66:67]
	s_add_u32 m0, s68, 28672
	s_nop 0
	global_load_lds_dwordx4 v105, s[66:67]
	s_add_u32 s64, s64, 0x80
	s_addc_u32 s65, s65, 0
	s_add_u32 s66, s66, 0x80
	s_addc_u32 s67, s67, 0
	ds_read_b128 v[64:67], v96 offset:32768
	ds_read_b128 v[68:71], v100 offset:32768
	ds_read_b128 v[72:75], v97 offset:32768
	ds_read_b128 v[76:79], v101 offset:32768
	ds_read_b128 v[80:83], v98 offset:32768
	ds_read_b128 v[84:87], v102 offset:32768
	ds_read_b128 v[88:91], v99 offset:32768
	ds_read_b128 v[92:95], v103 offset:32768
	s_waitcnt lgkmcnt(6)
	v_mfma_f32_32x32x16_bf16 v[2:17], v[64:67], v[68:71], v[2:17]
	s_waitcnt lgkmcnt(4)
	v_mfma_f32_32x32x16_bf16 v[2:17], v[72:75], v[76:79], v[2:17]
	s_waitcnt lgkmcnt(2)
	v_mfma_f32_32x32x16_bf16 v[2:17], v[80:83], v[84:87], v[2:17]
	s_waitcnt lgkmcnt(0)
	v_mfma_f32_32x32x16_bf16 v[2:17], v[88:91], v[92:95], v[2:17]
	s_waitcnt vmcnt(8)
	s_barrier
	s_add_u32 m0, s68, 32768
	s_nop 0
	global_load_lds_dwordx4 v104, s[64:65]
	s_add_u32 m0, s68, 36864
	s_nop 0
	global_load_lds_dwordx4 v105, s[64:65]
	s_add_u32 m0, s68, 40960
	s_nop 0
	global_load_lds_dwordx4 v104, s[66:67]
	s_add_u32 m0, s68, 45056
	s_nop 0
	global_load_lds_dwordx4 v105, s[66:67]
	s_add_u32 s64, s64, 0x80
	s_addc_u32 s65, s65, 0
	s_add_u32 s66, s66, 0x80
	s_addc_u32 s67, s67, 0
	ds_read_b128 v[64:67], v96 offset:49152
	ds_read_b128 v[68:71], v100 offset:49152
	ds_read_b128 v[72:75], v97 offset:49152
	ds_read_b128 v[76:79], v101 offset:49152
	ds_read_b128 v[80:83], v98 offset:49152
	ds_read_b128 v[84:87], v102 offset:49152
	ds_read_b128 v[88:91], v99 offset:49152
	ds_read_b128 v[92:95], v103 offset:49152
	s_waitcnt lgkmcnt(6)
	v_mfma_f32_32x32x16_bf16 v[2:17], v[64:67], v[68:71], v[2:17]
	s_waitcnt lgkmcnt(4)
	v_mfma_f32_32x32x16_bf16 v[2:17], v[72:75], v[76:79], v[2:17]
	s_waitcnt lgkmcnt(2)
	v_mfma_f32_32x32x16_bf16 v[2:17], v[80:83], v[84:87], v[2:17]
	s_waitcnt lgkmcnt(0)
	v_mfma_f32_32x32x16_bf16 v[2:17], v[88:91], v[92:95], v[2:17]
	s_sub_u32 s69, s69, 1
	s_cmp_lg_u32 s69, 0
	s_cbranch_scc1 .Ldc2_kloop
	s_waitcnt vmcnt(8)
	s_barrier
	s_add_u32 m0, s68, 49152
	s_nop 0
	global_load_lds_dwordx4 v104, s[64:65]
	s_add_u32 m0, s68, 53248
	s_nop 0
	global_load_lds_dwordx4 v105, s[64:65]
	s_add_u32 m0, s68, 57344
	s_nop 0
	global_load_lds_dwordx4 v104, s[66:67]
	s_add_u32 m0, s68, 61440
	s_nop 0
	global_load_lds_dwordx4 v105, s[66:67]
	s_add_u32 s64, s64, 0x80
	s_addc_u32 s65, s65, 0
	s_add_u32 s66, s66, 0x80
	s_addc_u32 s67, s67, 0
	ds_read_b128 v[64:67], v96 offset:0
	ds_read_b128 v[68:71], v100 offset:0
	ds_read_b128 v[72:75], v97 offset:0
	ds_read_b128 v[76:79], v101 offset:0
	ds_read_b128 v[80:83], v98 offset:0
	ds_read_b128 v[84:87], v102 offset:0
	ds_read_b128 v[88:91], v99 offset:0
	ds_read_b128 v[92:95], v103 offset:0
	s_waitcnt lgkmcnt(6)
	v_mfma_f32_32x32x16_bf16 v[2:17], v[64:67], v[68:71], v[2:17]
	s_waitcnt lgkmcnt(4)
	v_mfma_f32_32x32x16_bf16 v[2:17], v[72:75], v[76:79], v[2:17]
	s_waitcnt lgkmcnt(2)
	v_mfma_f32_32x32x16_bf16 v[2:17], v[80:83], v[84:87], v[2:17]
	s_waitcnt lgkmcnt(0)
	v_mfma_f32_32x32x16_bf16 v[2:17], v[88:91], v[92:95], v[2:17]
	s_waitcnt vmcnt(8)
	s_barrier
	ds_read_b128 v[64:67], v96 offset:16384
	ds_read_b128 v[68:71], v100 offset:16384
	ds_read_b128 v[72:75], v97 offset:16384
	ds_read_b128 v[76:79], v101 offset:16384
	ds_read_b128 v[80:83], v98 offset:16384
	ds_read_b128 v[84:87], v102 offset:16384
	ds_read_b128 v[88:91], v99 offset:16384
	ds_read_b128 v[92:95], v103 offset:16384
	s_waitcnt lgkmcnt(6)
	v_mfma_f32_32x32x16_bf16 v[2:17], v[64:67], v[68:71], v[2:17]
	s_waitcnt lgkmcnt(4)
	v_mfma_f32_32x32x16_bf16 v[2:17], v[72:75], v[76:79], v[2:17]
	s_waitcnt lgkmcnt(2)
	v_mfma_f32_32x32x16_bf16 v[2:17], v[80:83], v[84:87], v[2:17]
	s_waitcnt lgkmcnt(0)
	v_mfma_f32_32x32x16_bf16 v[2:17], v[88:91], v[92:95], v[2:17]
	s_waitcnt vmcnt(4)
	s_barrier
	ds_read_b128 v[64:67], v96 offset:32768
	ds_read_b128 v[68:71], v100 offset:32768
	ds_read_b128 v[72:75], v97 offset:32768
	ds_read_b128 v[76:79], v101 offset:32768
	ds_read_b128 v[80:83], v98 offset:32768
	ds_read_b128 v[84:87], v102 offset:32768
	ds_read_b128 v[88:91], v99 offset:32768
	ds_read_b128 v[92:95], v103 offset:32768
	s_waitcnt lgkmcnt(6)
	v_mfma_f32_32x32x16_bf16 v[2:17], v[64:67], v[68:71], v[2:17]
	s_waitcnt lgkmcnt(4)
	v_mfma_f32_32x32x16_bf16 v[2:17], v[72:75], v[76:79], v[2:17]
	s_waitcnt lgkmcnt(2)
	v_mfma_f32_32x32x16_bf16 v[2:17], v[80:83], v[84:87], v[2:17]
	s_waitcnt lgkmcnt(0)
	v_mfma_f32_32x32x16_bf16 v[2:17], v[88:91], v[92:95], v[2:17]
	s_waitcnt vmcnt(0)
	s_barrier
; #define GAS __attribute__((address_space(1)))
; DI int opaque0() { int z = 0; asm volatile("" : "+v"(z)); return z; }
; template <int AI, int BI>
; DI void dn_tile(const Params& p, char* wsb, int layer, int sub, bool final_out, int m0, int n0, char* lds) {
;     ...
;   const int m0e = m0 + opaque0();
;   const int mr = m0 < TL ? (m0 >> 11) : 8;
;   const float* gate = mods + (size_t)mr * 9216 + (2 + 6 * sub) * 1024;
;   GAS float* xsu = uptr(xs);
;   GAS float* outu = uptr(p.out);
; #pragma unroll
;   for (int bi = 0; bi < BI; ++bi) {
;     const int n = n0 + wb * 32 * BI + bi * 32 + r;
;     const float gv = 0.5f * gate[n];
;     const unsigned ib = (unsigned)((m0e + wa * 32 * AI + 4 * h) * 1024 + n);
; #pragma unroll
;     for (int ai = 0; ai < AI; ++ai)
; #pragma unroll
;       for (int reg = 0; reg < 16; ++reg) {
;         const unsigned idx = ib + (unsigned)((ai * 32 + (reg & 3) + 8 * (reg >> 2)) * 1024);
;         float v = xsu[idx] + gv * acc[ai][bi][reg];
;         if (final_out) outu[idx] = v; else xsu[idx] = v;
;         if ((reg & 7) == 7) __builtin_amdgcn_sched_barrier(0);
;       }
;   }
	ds_read_b128 v[64:67], v96 offset:49152
	ds_read_b128 v[68:71], v100 offset:49152
	ds_read_b128 v[72:75], v97 offset:49152
	ds_read_b128 v[76:79], v101 offset:49152
	ds_read_b128 v[80:83], v98 offset:49152
	ds_read_b128 v[84:87], v102 offset:49152
	ds_read_b128 v[88:91], v99 offset:49152
	ds_read_b128 v[92:95], v103 offset:49152
	s_waitcnt lgkmcnt(6)
	v_mfma_f32_32x32x16_bf16 v[2:17], v[64:67], v[68:71], v[2:17]
	s_waitcnt lgkmcnt(4)
	v_mfma_f32_32x32x16_bf16 v[2:17], v[72:75], v[76:79], v[2:17]
	s_waitcnt lgkmcnt(2)
	v_mfma_f32_32x32x16_bf16 v[2:17], v[80:83], v[84:87], v[2:17]
	s_waitcnt lgkmcnt(0)
	v_mfma_f32_32x32x16_bf16 v[2:17], v[88:91], v[92:95], v[2:17]
	s_nop 7
	s_nop 7
	v_and_b32_e32 v143, 31, v178
	v_lshrrev_b32_e32 v140, 1, v178
	v_and_b32_e32 v140, 32, v140
	v_or_b32_e32 v140, v140, v143
	v_bfe_u32 v143, v178, 5, 1
	v_bfe_u32 v139, v178, 7, 1
	v_lshlrev_b32_e32 v139, 5, v139
	v_lshl_add_u32 v139, v143, 2, v139
	v_lshl_add_u32 v139, v139, 10, v140
	v_lshlrev_b32_e32 v139, 2, v139
	v_add_u32_e32 v140, s71, v140
	v_lshlrev_b32_e32 v140, 2, v140
	global_load_dword v141, v140, s[6:7]
	s_lshl_b32 s82, s70, 10
	s_add_u32 s82, s82, s71
	s_lshl_b32 s82, s82, 2
	s_add_u32 s54, s8, s82
	s_addc_u32 s55, s9, 0
	s_mov_b64 s[80:81], s[54:55]
	global_load_dword v66, v139, s[80:81]
	s_add_u32 s80, s80, 4096
	s_addc_u32 s81, s81, 0
	global_load_dword v67, v139, s[80:81]
	s_add_u32 s80, s80, 4096
	s_addc_u32 s81, s81, 0
	global_load_dword v68, v139, s[80:81]
	s_add_u32 s80, s80, 4096
	s_addc_u32 s81, s81, 0
	global_load_dword v69, v139, s[80:81]
	s_add_u32 s80, s80, 20480
	s_addc_u32 s81, s81, 0
	global_load_dword v70, v139, s[80:81]
	s_add_u32 s80, s80, 4096
	s_addc_u32 s81, s81, 0
	global_load_dword v71, v139, s[80:81]
	s_add_u32 s80, s80, 4096
	s_addc_u32 s81, s81, 0
	global_load_dword v72, v139, s[80:81]
	s_add_u32 s80, s80, 4096
	s_addc_u32 s81, s81, 0
	global_load_dword v73, v139, s[80:81]
	s_add_u32 s80, s80, 20480
	s_addc_u32 s81, s81, 0
	global_load_dword v74, v139, s[80:81]
	s_add_u32 s80, s80, 4096
	s_addc_u32 s81, s81, 0
	global_load_dword v75, v139, s[80:81]
	s_add_u32 s80, s80, 4096
	s_addc_u32 s81, s81, 0
	global_load_dword v76, v139, s[80:81]
	s_add_u32 s80, s80, 4096
	s_addc_u32 s81, s81, 0
	global_load_dword v77, v139, s[80:81]
	s_add_u32 s80, s80, 20480
	s_addc_u32 s81, s81, 0
	global_load_dword v78, v139, s[80:81]
	s_add_u32 s80, s80, 4096
	s_addc_u32 s81, s81, 0
	global_load_dword v79, v139, s[80:81]
	s_add_u32 s80, s80, 4096
	s_addc_u32 s81, s81, 0
	global_load_dword v80, v139, s[80:81]
	s_add_u32 s80, s80, 4096
	s_addc_u32 s81, s81, 0
	global_load_dword v81, v139, s[80:81]
	s_waitcnt vmcnt(0)
	v_mul_f32_e32 v141, 0.5, v141
	v_fmac_f32_e32 v66, v2, v141
	v_fmac_f32_e32 v67, v3, v141
	v_fmac_f32_e32 v68, v4, v141
	v_fmac_f32_e32 v69, v5, v141
	v_fmac_f32_e32 v70, v6, v141
	v_fmac_f32_e32 v71, v7, v141
	v_fmac_f32_e32 v72, v8, v141
	v_fmac_f32_e32 v73, v9, v141
	v_fmac_f32_e32 v74, v10, v141
	v_fmac_f32_e32 v75, v11, v141
	v_fmac_f32_e32 v76, v12, v141
	v_fmac_f32_e32 v77, v13, v141
	v_fmac_f32_e32 v78, v14, v141
	v_fmac_f32_e32 v79, v15, v141
	v_fmac_f32_e32 v80, v16, v141
	v_fmac_f32_e32 v81, v17, v141
	s_mov_b64 s[80:81], s[54:55]
	global_store_dword v139, v66, s[80:81]
	s_add_u32 s80, s80, 4096
	s_addc_u32 s81, s81, 0
	global_store_dword v139, v67, s[80:81]
	s_add_u32 s80, s80, 4096
	s_addc_u32 s81, s81, 0
	global_store_dword v139, v68, s[80:81]
	s_add_u32 s80, s80, 4096
	s_addc_u32 s81, s81, 0
	global_store_dword v139, v69, s[80:81]
	s_add_u32 s80, s80, 20480
	s_addc_u32 s81, s81, 0
	global_store_dword v139, v70, s[80:81]
	s_add_u32 s80, s80, 4096
	s_addc_u32 s81, s81, 0
	global_store_dword v139, v71, s[80:81]
	s_add_u32 s80, s80, 4096
	s_addc_u32 s81, s81, 0
	global_store_dword v139, v72, s[80:81]
	s_add_u32 s80, s80, 4096
	s_addc_u32 s81, s81, 0
	global_store_dword v139, v73, s[80:81]
	s_add_u32 s80, s80, 20480
	s_addc_u32 s81, s81, 0
	global_store_dword v139, v74, s[80:81]
	s_add_u32 s80, s80, 4096
	s_addc_u32 s81, s81, 0
	global_store_dword v139, v75, s[80:81]
	s_add_u32 s80, s80, 4096
	s_addc_u32 s81, s81, 0
	global_store_dword v139, v76, s[80:81]
	s_add_u32 s80, s80, 4096
	s_addc_u32 s81, s81, 0
	global_store_dword v139, v77, s[80:81]
	s_add_u32 s80, s80, 20480
	s_addc_u32 s81, s81, 0
	global_store_dword v139, v78, s[80:81]
	s_add_u32 s80, s80, 4096
	s_addc_u32 s81, s81, 0
	global_store_dword v139, v79, s[80:81]
	s_add_u32 s80, s80, 4096
	s_addc_u32 s81, s81, 0
	global_store_dword v139, v80, s[80:81]
	s_add_u32 s80, s80, 4096
	s_addc_u32 s81, s81, 0
	global_store_dword v139, v81, s[80:81]
	s_branch .LBB0_1527
